# w_o and down-GEMM epilogues hand-written with deeper load prefetch (ring of 4 row buffers / all rows up front)
# baseline (speedup 1.0000x reference)
; __device__ __forceinline__ u32x4 pack8(const f32x4 a, const f32x4 b) { u32x4 w; w.x = cvt_pk_bf16(a[0], a[1]); w.y = cvt_pk_bf16(a[2], a[3]); w.z = cvt_pk_bf16(b[0], b[1]); w.w = cvt_pk_bf16(b[2], b[3]); return w; }
;     __device__ __forceinline__ void operator()(const f32x4 (&acc)[2][2][4][2], const pg8::Unit& u, int wr, int wc, int fr, int fq) const {
;         const int row0 = u.pm * 256 + wr * 64 + fr, col0 = u.pn * 256 + wc * 32 + 8 * fq;
; #pragma unroll
;         for (int ai = 0; ai < 2; ++ai)
; #pragma unroll
;             for (int mp = 0; mp < 2; ++mp) {
;                 f32x4 xr[2][2][2]; float iqv[2];
; #pragma unroll
;                 for (int mm = 0; mm < 2; ++mm) { const int row = row0 + ai * 128 + (2 * mp + mm) * 16; iqv[mm] = rs0[row];
; #pragma unroll
;                     for (int bj = 0; bj < 2; ++bj) { const size_t off = (size_t)row * DM + col0 + bj * 128; xr[mm][bj][0] = *(const f32x4*)(x + off); xr[mm][bj][1] = *(const f32x4*)(x + off + 4); } }
; #pragma unroll
;                 for (int mm = 0; mm < 2; ++mm) { const int m = 2 * mp + mm, row = row0 + ai * 128 + m * 16; float ss = 0.f; const float iq = (127.f / QCLIP) * iqv[mm];
; #pragma unroll
;                     for (int bj = 0; bj < 2; ++bj) { const size_t off = (size_t)row * DM + col0 + bj * 128;
;                         const f32x4 h0 = xr[mm][bj][0] + acc[ai][bj][m][0], h1 = xr[mm][bj][1] + acc[ai][bj][m][1];
;                         *(u32x4*)(HB + off) = pack8(h0, h1);
;                         { f32x4 q0, q1;
; #pragma unroll
;                           for (int ee = 0; ee < 4; ++ee) { q0[ee] = fminf(fmaxf(rintf(h0[ee] * iq), -127.f), 127.f); q1[ee] = fminf(fmaxf(rintf(h1[ee] * iq), -127.f), 127.f); }
;                           *(u32x2*)(HQ + off) = pack8_i8(q0, q1); }
;                         ss += (h0[0] * h0[0] + h0[1] * h0[1]) + (h0[2] * h0[2] + h0[3] * h0[3]) + (h1[0] * h1[0] + h1[1] * h1[1]) + (h1[2] * h1[2] + h1[3] * h1[3]); }
;                     ss += __shfl_xor(ss, 16); ss += __shfl_xor(ss, 32);
;                     if (fq == 0) unsafeAtomicAdd(rss1 + row, ss); }
;                 asm volatile("" ::: "memory"); }
.LBB0_1137:
	v_sub_u32_e32 v140, v162, v1
	s_mov_b32 s99, s50
	v_readfirstlane_b32 s98, v140
	s_lshr_b32 s98, s98, 8
	v_lshlrev_b32_e32 v134, 2, v1
	v_lshlrev_b32_e32 v135, 14, v1
	v_lshlrev_b32_e32 v136, 13, v1
	v_lshlrev_b32_e32 v137, 12, v1
	v_lshl_add_u32 v135, v180, 2, v135
	v_lshl_add_u32 v136, v180, 1, v136
	v_add_u32_e32 v137, v137, v180
	v_xor_b32_e32 v138, 16, v184
	v_xor_b32_e32 v139, 32, v184
	v_lshlrev_b32_e32 v138, 2, v138
	v_lshlrev_b32_e32 v139, 2, v139
	s_lshl_b32 s12, s98, 10
	s_add_u32 s14, s36, s12
	s_addc_u32 s15, s37, 0
	s_add_u32 s16, s30, s12
	s_addc_u32 s17, s31, 0
	s_lshl_b32 s12, s98, 22
	s_lshl_b32 s13, s99, 10
	s_add_u32 s12, s12, s13
	s_add_u32 s84, s22, s12
	s_addc_u32 s85, s23, 0
	s_lshr_b32 s13, s12, 1
	s_add_u32 s86, s26, s13
	s_addc_u32 s87, s27, 0
	s_lshr_b32 s13, s12, 2
	s_add_u32 s88, s34, s13
	s_addc_u32 s89, s35, 0
	global_load_dword v168, v134, s[14:15]
	global_load_dwordx4 v[186:189], v135, s[84:85]
	global_load_dwordx4 v[190:193], v135, s[84:85] offset:16
	global_load_dwordx4 v[194:197], v135, s[84:85] offset:512
	global_load_dwordx4 v[198:201], v135, s[84:85] offset:528
	s_add_u32 s84, s84, 0x40000
	s_addc_u32 s85, s85, 0
	global_load_dword v169, v134, s[14:15] offset:64
	global_load_dwordx4 v[202:205], v135, s[84:85]
	global_load_dwordx4 v[206:209], v135, s[84:85] offset:16
	global_load_dwordx4 v[210:213], v135, s[84:85] offset:512
	global_load_dwordx4 v[214:217], v135, s[84:85] offset:528
	s_add_u32 s84, s84, 0x40000
	s_addc_u32 s85, s85, 0
	global_load_dword v170, v134, s[14:15] offset:128
	global_load_dwordx4 v[218:221], v135, s[84:85]
	global_load_dwordx4 v[222:225], v135, s[84:85] offset:16
	global_load_dwordx4 v[226:229], v135, s[84:85] offset:512
	global_load_dwordx4 v[230:233], v135, s[84:85] offset:528
	s_add_u32 s84, s84, 0x40000
	s_addc_u32 s85, s85, 0
	global_load_dword v171, v134, s[14:15] offset:192
	global_load_dwordx4 v[234:237], v135, s[84:85]
	global_load_dwordx4 v[238:241], v135, s[84:85] offset:16
	global_load_dwordx4 v[242:245], v135, s[84:85] offset:512
	global_load_dwordx4 v[246:249], v135, s[84:85] offset:528
	s_add_u32 s84, s84, 0x140000
	s_addc_u32 s85, s85, 0
	s_waitcnt vmcnt(15)
	v_mul_f32_e32 v140, 0x41e1c71c, v168
	v_pk_add_f32 v[130:131], v[130:131], v[186:187]
	v_pk_add_f32 v[132:133], v[132:133], v[188:189]
	v_cvt_pk_bf16_f32 v144, v130, v131
	v_cvt_pk_bf16_f32 v145, v132, v133
	v_mul_f32_e32 v250, v140, v130
	v_mul_f32_e32 v251, v140, v131
	v_mul_f32_e32 v252, v140, v132
	v_mul_f32_e32 v253, v140, v133
	v_rndne_f32_e32 v250, v250
	v_rndne_f32_e32 v251, v251
	v_rndne_f32_e32 v252, v252
	v_rndne_f32_e32 v253, v253
	v_med3_f32 v250, v250, s71, v183
	v_med3_f32 v251, v251, s71, v183
	v_med3_f32 v252, v252, s71, v183
	v_med3_f32 v253, v253, s71, v183
	v_cvt_i32_f32_e32 v250, v250
	v_cvt_i32_f32_e32 v251, v251
	v_cvt_i32_f32_e32 v252, v252
	v_cvt_i32_f32_e32 v253, v253
	v_and_b32_e32 v250, 0xff, v250
	v_and_b32_e32 v251, 0xff, v251
	v_and_b32_e32 v252, 0xff, v252
	v_lshl_or_b32 v250, v251, 8, v250
	v_lshl_or_b32 v250, v252, 16, v250
	v_lshl_or_b32 v142, v253, 24, v250
	v_pk_mul_f32 v[164:165], v[130:131], v[130:131]
	v_pk_mul_f32 v[166:167], v[132:133], v[132:133]
	v_pk_add_f32 v[126:127], v[126:127], v[190:191]
	v_pk_add_f32 v[128:129], v[128:129], v[192:193]
	v_cvt_pk_bf16_f32 v146, v126, v127
	v_cvt_pk_bf16_f32 v147, v128, v129
	v_mul_f32_e32 v250, v140, v126
	v_mul_f32_e32 v251, v140, v127
	v_mul_f32_e32 v252, v140, v128
	v_mul_f32_e32 v253, v140, v129
	v_rndne_f32_e32 v250, v250
	v_rndne_f32_e32 v251, v251
	v_rndne_f32_e32 v252, v252
	v_rndne_f32_e32 v253, v253
	v_med3_f32 v250, v250, s71, v183
	v_med3_f32 v251, v251, s71, v183
	v_med3_f32 v252, v252, s71, v183
	v_med3_f32 v253, v253, s71, v183
	v_cvt_i32_f32_e32 v250, v250
	v_cvt_i32_f32_e32 v251, v251
	v_cvt_i32_f32_e32 v252, v252
	v_cvt_i32_f32_e32 v253, v253
	v_and_b32_e32 v250, 0xff, v250
	v_and_b32_e32 v251, 0xff, v251
	v_and_b32_e32 v252, 0xff, v252
	v_lshl_or_b32 v250, v251, 8, v250
	v_lshl_or_b32 v250, v252, 16, v250
	v_lshl_or_b32 v143, v253, 24, v250
	v_pk_fma_f32 v[164:165], v[126:127], v[126:127], v[164:165]
	v_pk_fma_f32 v[166:167], v[128:129], v[128:129], v[166:167]
	global_store_dwordx4 v136, v[144:147], s[86:87]
	global_store_dwordx2 v137, v[142:143], s[88:89]
	s_nop 0
	v_pk_add_f32 v[122:123], v[122:123], v[194:195]
	v_pk_add_f32 v[124:125], v[124:125], v[196:197]
	v_cvt_pk_bf16_f32 v144, v122, v123
	v_cvt_pk_bf16_f32 v145, v124, v125
	v_mul_f32_e32 v250, v140, v122
	v_mul_f32_e32 v251, v140, v123
	v_mul_f32_e32 v252, v140, v124
	v_mul_f32_e32 v253, v140, v125
	v_rndne_f32_e32 v250, v250
	v_rndne_f32_e32 v251, v251
	v_rndne_f32_e32 v252, v252
	v_rndne_f32_e32 v253, v253
	v_med3_f32 v250, v250, s71, v183
	v_med3_f32 v251, v251, s71, v183
	v_med3_f32 v252, v252, s71, v183
	v_med3_f32 v253, v253, s71, v183
	v_cvt_i32_f32_e32 v250, v250
	v_cvt_i32_f32_e32 v251, v251
	v_cvt_i32_f32_e32 v252, v252
	v_cvt_i32_f32_e32 v253, v253
	v_and_b32_e32 v250, 0xff, v250
	v_and_b32_e32 v251, 0xff, v251
	v_and_b32_e32 v252, 0xff, v252
	v_lshl_or_b32 v250, v251, 8, v250
	v_lshl_or_b32 v250, v252, 16, v250
	v_lshl_or_b32 v142, v253, 24, v250
	v_pk_fma_f32 v[164:165], v[122:123], v[122:123], v[164:165]
	v_pk_fma_f32 v[166:167], v[124:125], v[124:125], v[166:167]
	v_pk_add_f32 v[118:119], v[118:119], v[198:199]
	v_pk_add_f32 v[120:121], v[120:121], v[200:201]
	v_cvt_pk_bf16_f32 v146, v118, v119
	v_cvt_pk_bf16_f32 v147, v120, v121
	v_mul_f32_e32 v250, v140, v118
	v_mul_f32_e32 v251, v140, v119
	v_mul_f32_e32 v252, v140, v120
	v_mul_f32_e32 v253, v140, v121
	v_rndne_f32_e32 v250, v250
	v_rndne_f32_e32 v251, v251
	v_rndne_f32_e32 v252, v252
	v_rndne_f32_e32 v253, v253
	v_med3_f32 v250, v250, s71, v183
	v_med3_f32 v251, v251, s71, v183
	v_med3_f32 v252, v252, s71, v183
	v_med3_f32 v253, v253, s71, v183
	v_cvt_i32_f32_e32 v250, v250
	v_cvt_i32_f32_e32 v251, v251
	v_cvt_i32_f32_e32 v252, v252
	v_cvt_i32_f32_e32 v253, v253
	v_and_b32_e32 v250, 0xff, v250
	v_and_b32_e32 v251, 0xff, v251
	v_and_b32_e32 v252, 0xff, v252
	v_lshl_or_b32 v250, v251, 8, v250
	v_lshl_or_b32 v250, v252, 16, v250
	v_lshl_or_b32 v143, v253, 24, v250
	v_pk_fma_f32 v[164:165], v[118:119], v[118:119], v[164:165]
	v_pk_fma_f32 v[166:167], v[120:121], v[120:121], v[166:167]
	global_store_dwordx4 v136, v[144:147], s[86:87] offset:256
	global_store_dwordx2 v137, v[142:143], s[88:89] offset:128
	s_nop 0
	v_add_f32_e32 v164, v164, v165
	v_add_f32_e32 v166, v166, v167
	v_add_f32_e32 v164, v164, v166
	ds_bpermute_b32 v165, v138, v164
	s_waitcnt lgkmcnt(0)
; __device__ __forceinline__ u32x4 pack8(const f32x4 a, const f32x4 b) { u32x4 w; w.x = cvt_pk_bf16(a[0], a[1]); w.y = cvt_pk_bf16(a[2], a[3]); w.z = cvt_pk_bf16(b[0], b[1]); w.w = cvt_pk_bf16(b[2], b[3]); return w; }
;     __device__ __forceinline__ void operator()(const f32x4 (&acc)[2][2][4][2], const pg8::Unit& u, int wr, int wc, int fr, int fq) const {
;         const int row0 = u.pm * 256 + wr * 64 + fr, col0 = u.pn * 256 + wc * 32 + 8 * fq;
; #pragma unroll
;         for (int ai = 0; ai < 2; ++ai)
; #pragma unroll
;             for (int mp = 0; mp < 2; ++mp) {
;                 f32x4 xr[2][2][2]; float iqv[2];
; #pragma unroll
;                 for (int mm = 0; mm < 2; ++mm) { const int row = row0 + ai * 128 + (2 * mp + mm) * 16; iqv[mm] = rs0[row];
; #pragma unroll
;                     for (int bj = 0; bj < 2; ++bj) { const size_t off = (size_t)row * DM + col0 + bj * 128; xr[mm][bj][0] = *(const f32x4*)(x + off); xr[mm][bj][1] = *(const f32x4*)(x + off + 4); } }
; #pragma unroll
;                 for (int mm = 0; mm < 2; ++mm) { const int m = 2 * mp + mm, row = row0 + ai * 128 + m * 16; float ss = 0.f; const float iq = (127.f / QCLIP) * iqv[mm];
; #pragma unroll
;                     for (int bj = 0; bj < 2; ++bj) { const size_t off = (size_t)row * DM + col0 + bj * 128;
;                         const f32x4 h0 = xr[mm][bj][0] + acc[ai][bj][m][0], h1 = xr[mm][bj][1] + acc[ai][bj][m][1];
;                         *(u32x4*)(HB + off) = pack8(h0, h1);
;                         { f32x4 q0, q1;
; #pragma unroll
;                           for (int ee = 0; ee < 4; ++ee) { q0[ee] = fminf(fmaxf(rintf(h0[ee] * iq), -127.f), 127.f); q1[ee] = fminf(fmaxf(rintf(h1[ee] * iq), -127.f), 127.f); }
;                           *(u32x2*)(HQ + off) = pack8_i8(q0, q1); }
;                         ss += (h0[0] * h0[0] + h0[1] * h0[1]) + (h0[2] * h0[2] + h0[3] * h0[3]) + (h1[0] * h1[0] + h1[1] * h1[1]) + (h1[2] * h1[2] + h1[3] * h1[3]); }
;                     ss += __shfl_xor(ss, 16); ss += __shfl_xor(ss, 32);
;                     if (fq == 0) unsafeAtomicAdd(rss1 + row, ss); }
;                 asm volatile("" ::: "memory"); }
	v_add_f32_e32 v164, v164, v165
	ds_bpermute_b32 v165, v139, v164
	s_waitcnt lgkmcnt(0)
	v_add_f32_e32 v164, v164, v165
	s_and_saveexec_b64 s[32:33], s[6:7]
	global_atomic_add_f32 v134, v164, s[16:17]
	s_or_b64 exec, exec, s[32:33]
	s_add_u32 s86, s86, 0x20000
	s_addc_u32 s87, s87, 0
	s_add_u32 s88, s88, 0x10000
	s_addc_u32 s89, s89, 0
	global_load_dword v168, v134, s[14:15] offset:512
	global_load_dwordx4 v[186:189], v135, s[84:85]
	global_load_dwordx4 v[190:193], v135, s[84:85] offset:16
	global_load_dwordx4 v[194:197], v135, s[84:85] offset:512
	global_load_dwordx4 v[198:201], v135, s[84:85] offset:528
	s_add_u32 s84, s84, 0x40000
	s_addc_u32 s85, s85, 0
	s_waitcnt vmcnt(20)
	v_mul_f32_e32 v140, 0x41e1c71c, v169
	v_pk_add_f32 v[114:115], v[114:115], v[202:203]
	v_pk_add_f32 v[116:117], v[116:117], v[204:205]
	v_cvt_pk_bf16_f32 v144, v114, v115
	v_cvt_pk_bf16_f32 v145, v116, v117
	v_mul_f32_e32 v250, v140, v114
	v_mul_f32_e32 v251, v140, v115
	v_mul_f32_e32 v252, v140, v116
	v_mul_f32_e32 v253, v140, v117
	v_rndne_f32_e32 v250, v250
	v_rndne_f32_e32 v251, v251
	v_rndne_f32_e32 v252, v252
	v_rndne_f32_e32 v253, v253
	v_med3_f32 v250, v250, s71, v183
	v_med3_f32 v251, v251, s71, v183
	v_med3_f32 v252, v252, s71, v183
	v_med3_f32 v253, v253, s71, v183
	v_cvt_i32_f32_e32 v250, v250
	v_cvt_i32_f32_e32 v251, v251
	v_cvt_i32_f32_e32 v252, v252
	v_cvt_i32_f32_e32 v253, v253
	v_and_b32_e32 v250, 0xff, v250
	v_and_b32_e32 v251, 0xff, v251
	v_and_b32_e32 v252, 0xff, v252
	v_lshl_or_b32 v250, v251, 8, v250
	v_lshl_or_b32 v250, v252, 16, v250
	v_lshl_or_b32 v142, v253, 24, v250
	v_pk_mul_f32 v[164:165], v[114:115], v[114:115]
	v_pk_mul_f32 v[166:167], v[116:117], v[116:117]
	v_pk_add_f32 v[110:111], v[110:111], v[206:207]
	v_pk_add_f32 v[112:113], v[112:113], v[208:209]
	v_cvt_pk_bf16_f32 v146, v110, v111
	v_cvt_pk_bf16_f32 v147, v112, v113
	v_mul_f32_e32 v250, v140, v110
	v_mul_f32_e32 v251, v140, v111
	v_mul_f32_e32 v252, v140, v112
	v_mul_f32_e32 v253, v140, v113
	v_rndne_f32_e32 v250, v250
	v_rndne_f32_e32 v251, v251
	v_rndne_f32_e32 v252, v252
	v_rndne_f32_e32 v253, v253
	v_med3_f32 v250, v250, s71, v183
	v_med3_f32 v251, v251, s71, v183
	v_med3_f32 v252, v252, s71, v183
	v_med3_f32 v253, v253, s71, v183
	v_cvt_i32_f32_e32 v250, v250
	v_cvt_i32_f32_e32 v251, v251
	v_cvt_i32_f32_e32 v252, v252
	v_cvt_i32_f32_e32 v253, v253
	v_and_b32_e32 v250, 0xff, v250
	v_and_b32_e32 v251, 0xff, v251
	v_and_b32_e32 v252, 0xff, v252
	v_lshl_or_b32 v250, v251, 8, v250
	v_lshl_or_b32 v250, v252, 16, v250
	v_lshl_or_b32 v143, v253, 24, v250
	v_pk_fma_f32 v[164:165], v[110:111], v[110:111], v[164:165]
	v_pk_fma_f32 v[166:167], v[112:113], v[112:113], v[166:167]
	global_store_dwordx4 v136, v[144:147], s[86:87]
	global_store_dwordx2 v137, v[142:143], s[88:89]
	s_nop 0
	v_pk_add_f32 v[106:107], v[106:107], v[210:211]
	v_pk_add_f32 v[108:109], v[108:109], v[212:213]
	v_cvt_pk_bf16_f32 v144, v106, v107
	v_cvt_pk_bf16_f32 v145, v108, v109
	v_mul_f32_e32 v250, v140, v106
	v_mul_f32_e32 v251, v140, v107
	v_mul_f32_e32 v252, v140, v108
	v_mul_f32_e32 v253, v140, v109
	v_rndne_f32_e32 v250, v250
	v_rndne_f32_e32 v251, v251
	v_rndne_f32_e32 v252, v252
	v_rndne_f32_e32 v253, v253
	v_med3_f32 v250, v250, s71, v183
	v_med3_f32 v251, v251, s71, v183
	v_med3_f32 v252, v252, s71, v183
	v_med3_f32 v253, v253, s71, v183
	v_cvt_i32_f32_e32 v250, v250
	v_cvt_i32_f32_e32 v251, v251
	v_cvt_i32_f32_e32 v252, v252
	v_cvt_i32_f32_e32 v253, v253
	v_and_b32_e32 v250, 0xff, v250
	v_and_b32_e32 v251, 0xff, v251
	v_and_b32_e32 v252, 0xff, v252
	v_lshl_or_b32 v250, v251, 8, v250
	v_lshl_or_b32 v250, v252, 16, v250
	v_lshl_or_b32 v142, v253, 24, v250
	v_pk_fma_f32 v[164:165], v[106:107], v[106:107], v[164:165]
	v_pk_fma_f32 v[166:167], v[108:109], v[108:109], v[166:167]
	v_pk_add_f32 v[102:103], v[102:103], v[214:215]
	v_pk_add_f32 v[104:105], v[104:105], v[216:217]
	v_cvt_pk_bf16_f32 v146, v102, v103
	v_cvt_pk_bf16_f32 v147, v104, v105
	v_mul_f32_e32 v250, v140, v102
	v_mul_f32_e32 v251, v140, v103
	v_mul_f32_e32 v252, v140, v104
	v_mul_f32_e32 v253, v140, v105
	v_rndne_f32_e32 v250, v250
	v_rndne_f32_e32 v251, v251
	v_rndne_f32_e32 v252, v252
	v_rndne_f32_e32 v253, v253
	v_med3_f32 v250, v250, s71, v183
	v_med3_f32 v251, v251, s71, v183
	v_med3_f32 v252, v252, s71, v183
	v_med3_f32 v253, v253, s71, v183
	v_cvt_i32_f32_e32 v250, v250
	v_cvt_i32_f32_e32 v251, v251
	v_cvt_i32_f32_e32 v252, v252
	v_cvt_i32_f32_e32 v253, v253
	v_and_b32_e32 v250, 0xff, v250
	v_and_b32_e32 v251, 0xff, v251
	v_and_b32_e32 v252, 0xff, v252
	v_lshl_or_b32 v250, v251, 8, v250
	v_lshl_or_b32 v250, v252, 16, v250
	v_lshl_or_b32 v143, v253, 24, v250
	v_pk_fma_f32 v[164:165], v[102:103], v[102:103], v[164:165]
	v_pk_fma_f32 v[166:167], v[104:105], v[104:105], v[166:167]
	global_store_dwordx4 v136, v[144:147], s[86:87] offset:256
	global_store_dwordx2 v137, v[142:143], s[88:89] offset:128
	s_nop 0
	v_add_f32_e32 v164, v164, v165
	v_add_f32_e32 v166, v166, v167
	v_add_f32_e32 v164, v164, v166
	ds_bpermute_b32 v165, v138, v164
	s_waitcnt lgkmcnt(0)
	v_add_f32_e32 v164, v164, v165
	ds_bpermute_b32 v165, v139, v164
	s_waitcnt lgkmcnt(0)
	v_add_f32_e32 v164, v164, v165
	s_and_saveexec_b64 s[32:33], s[6:7]
	global_atomic_add_f32 v134, v164, s[16:17] offset:64
	s_or_b64 exec, exec, s[32:33]
	s_add_u32 s86, s86, 0x20000
	s_addc_u32 s87, s87, 0
	s_add_u32 s88, s88, 0x10000
	s_addc_u32 s89, s89, 0
	global_load_dword v169, v134, s[14:15] offset:576
	global_load_dwordx4 v[202:205], v135, s[84:85]
	global_load_dwordx4 v[206:209], v135, s[84:85] offset:16
	global_load_dwordx4 v[210:213], v135, s[84:85] offset:512
	global_load_dwordx4 v[214:217], v135, s[84:85] offset:528
	s_add_u32 s84, s84, 0x40000
	s_addc_u32 s85, s85, 0
	s_waitcnt vmcnt(25)
; __device__ __forceinline__ u32x4 pack8(const f32x4 a, const f32x4 b) { u32x4 w; w.x = cvt_pk_bf16(a[0], a[1]); w.y = cvt_pk_bf16(a[2], a[3]); w.z = cvt_pk_bf16(b[0], b[1]); w.w = cvt_pk_bf16(b[2], b[3]); return w; }
;     __device__ __forceinline__ void operator()(const f32x4 (&acc)[2][2][4][2], const pg8::Unit& u, int wr, int wc, int fr, int fq) const {
;         const int row0 = u.pm * 256 + wr * 64 + fr, col0 = u.pn * 256 + wc * 32 + 8 * fq;
; #pragma unroll
;         for (int ai = 0; ai < 2; ++ai)
; #pragma unroll
;             for (int mp = 0; mp < 2; ++mp) {
;                 f32x4 xr[2][2][2]; float iqv[2];
; #pragma unroll
;                 for (int mm = 0; mm < 2; ++mm) { const int row = row0 + ai * 128 + (2 * mp + mm) * 16; iqv[mm] = rs0[row];
; #pragma unroll
;                     for (int bj = 0; bj < 2; ++bj) { const size_t off = (size_t)row * DM + col0 + bj * 128; xr[mm][bj][0] = *(const f32x4*)(x + off); xr[mm][bj][1] = *(const f32x4*)(x + off + 4); } }
; #pragma unroll
;                 for (int mm = 0; mm < 2; ++mm) { const int m = 2 * mp + mm, row = row0 + ai * 128 + m * 16; float ss = 0.f; const float iq = (127.f / QCLIP) * iqv[mm];
; #pragma unroll
;                     for (int bj = 0; bj < 2; ++bj) { const size_t off = (size_t)row * DM + col0 + bj * 128;
;                         const f32x4 h0 = xr[mm][bj][0] + acc[ai][bj][m][0], h1 = xr[mm][bj][1] + acc[ai][bj][m][1];
;                         *(u32x4*)(HB + off) = pack8(h0, h1);
;                         { f32x4 q0, q1;
; #pragma unroll
;                           for (int ee = 0; ee < 4; ++ee) { q0[ee] = fminf(fmaxf(rintf(h0[ee] * iq), -127.f), 127.f); q1[ee] = fminf(fmaxf(rintf(h1[ee] * iq), -127.f), 127.f); }
;                           *(u32x2*)(HQ + off) = pack8_i8(q0, q1); }
;                         ss += (h0[0] * h0[0] + h0[1] * h0[1]) + (h0[2] * h0[2] + h0[3] * h0[3]) + (h1[0] * h1[0] + h1[1] * h1[1]) + (h1[2] * h1[2] + h1[3] * h1[3]); }
;                     ss += __shfl_xor(ss, 16); ss += __shfl_xor(ss, 32);
;                     if (fq == 0) unsafeAtomicAdd(rss1 + row, ss); }
;                 asm volatile("" ::: "memory"); }
	v_mul_f32_e32 v140, 0x41e1c71c, v170
	v_pk_add_f32 v[98:99], v[98:99], v[218:219]
	v_pk_add_f32 v[100:101], v[100:101], v[220:221]
	v_cvt_pk_bf16_f32 v144, v98, v99
	v_cvt_pk_bf16_f32 v145, v100, v101
	v_mul_f32_e32 v250, v140, v98
	v_mul_f32_e32 v251, v140, v99
	v_mul_f32_e32 v252, v140, v100
	v_mul_f32_e32 v253, v140, v101
	v_rndne_f32_e32 v250, v250
	v_rndne_f32_e32 v251, v251
	v_rndne_f32_e32 v252, v252
	v_rndne_f32_e32 v253, v253
	v_med3_f32 v250, v250, s71, v183
	v_med3_f32 v251, v251, s71, v183
	v_med3_f32 v252, v252, s71, v183
	v_med3_f32 v253, v253, s71, v183
	v_cvt_i32_f32_e32 v250, v250
	v_cvt_i32_f32_e32 v251, v251
	v_cvt_i32_f32_e32 v252, v252
	v_cvt_i32_f32_e32 v253, v253
	v_and_b32_e32 v250, 0xff, v250
	v_and_b32_e32 v251, 0xff, v251
	v_and_b32_e32 v252, 0xff, v252
	v_lshl_or_b32 v250, v251, 8, v250
	v_lshl_or_b32 v250, v252, 16, v250
	v_lshl_or_b32 v142, v253, 24, v250
	v_pk_mul_f32 v[164:165], v[98:99], v[98:99]
	v_pk_mul_f32 v[166:167], v[100:101], v[100:101]
	v_pk_add_f32 v[94:95], v[94:95], v[222:223]
	v_pk_add_f32 v[96:97], v[96:97], v[224:225]
	v_cvt_pk_bf16_f32 v146, v94, v95
	v_cvt_pk_bf16_f32 v147, v96, v97
	v_mul_f32_e32 v250, v140, v94
	v_mul_f32_e32 v251, v140, v95
	v_mul_f32_e32 v252, v140, v96
	v_mul_f32_e32 v253, v140, v97
	v_rndne_f32_e32 v250, v250
	v_rndne_f32_e32 v251, v251
	v_rndne_f32_e32 v252, v252
	v_rndne_f32_e32 v253, v253
	v_med3_f32 v250, v250, s71, v183
	v_med3_f32 v251, v251, s71, v183
	v_med3_f32 v252, v252, s71, v183
	v_med3_f32 v253, v253, s71, v183
	v_cvt_i32_f32_e32 v250, v250
	v_cvt_i32_f32_e32 v251, v251
	v_cvt_i32_f32_e32 v252, v252
	v_cvt_i32_f32_e32 v253, v253
	v_and_b32_e32 v250, 0xff, v250
	v_and_b32_e32 v251, 0xff, v251
	v_and_b32_e32 v252, 0xff, v252
	v_lshl_or_b32 v250, v251, 8, v250
	v_lshl_or_b32 v250, v252, 16, v250
	v_lshl_or_b32 v143, v253, 24, v250
	v_pk_fma_f32 v[164:165], v[94:95], v[94:95], v[164:165]
	v_pk_fma_f32 v[166:167], v[96:97], v[96:97], v[166:167]
	global_store_dwordx4 v136, v[144:147], s[86:87]
	global_store_dwordx2 v137, v[142:143], s[88:89]
	s_nop 0
	v_pk_add_f32 v[90:91], v[90:91], v[226:227]
	v_pk_add_f32 v[92:93], v[92:93], v[228:229]
	v_cvt_pk_bf16_f32 v144, v90, v91
	v_cvt_pk_bf16_f32 v145, v92, v93
	v_mul_f32_e32 v250, v140, v90
	v_mul_f32_e32 v251, v140, v91
	v_mul_f32_e32 v252, v140, v92
	v_mul_f32_e32 v253, v140, v93
	v_rndne_f32_e32 v250, v250
	v_rndne_f32_e32 v251, v251
	v_rndne_f32_e32 v252, v252
	v_rndne_f32_e32 v253, v253
	v_med3_f32 v250, v250, s71, v183
	v_med3_f32 v251, v251, s71, v183
	v_med3_f32 v252, v252, s71, v183
	v_med3_f32 v253, v253, s71, v183
	v_cvt_i32_f32_e32 v250, v250
	v_cvt_i32_f32_e32 v251, v251
	v_cvt_i32_f32_e32 v252, v252
	v_cvt_i32_f32_e32 v253, v253
	v_and_b32_e32 v250, 0xff, v250
	v_and_b32_e32 v251, 0xff, v251
	v_and_b32_e32 v252, 0xff, v252
	v_lshl_or_b32 v250, v251, 8, v250
	v_lshl_or_b32 v250, v252, 16, v250
	v_lshl_or_b32 v142, v253, 24, v250
	v_pk_fma_f32 v[164:165], v[90:91], v[90:91], v[164:165]
	v_pk_fma_f32 v[166:167], v[92:93], v[92:93], v[166:167]
	v_pk_add_f32 v[86:87], v[86:87], v[230:231]
	v_pk_add_f32 v[88:89], v[88:89], v[232:233]
	v_cvt_pk_bf16_f32 v146, v86, v87
	v_cvt_pk_bf16_f32 v147, v88, v89
	v_mul_f32_e32 v250, v140, v86
	v_mul_f32_e32 v251, v140, v87
	v_mul_f32_e32 v252, v140, v88
	v_mul_f32_e32 v253, v140, v89
	v_rndne_f32_e32 v250, v250
	v_rndne_f32_e32 v251, v251
	v_rndne_f32_e32 v252, v252
	v_rndne_f32_e32 v253, v253
	v_med3_f32 v250, v250, s71, v183
	v_med3_f32 v251, v251, s71, v183
	v_med3_f32 v252, v252, s71, v183
	v_med3_f32 v253, v253, s71, v183
	v_cvt_i32_f32_e32 v250, v250
	v_cvt_i32_f32_e32 v251, v251
	v_cvt_i32_f32_e32 v252, v252
	v_cvt_i32_f32_e32 v253, v253
	v_and_b32_e32 v250, 0xff, v250
	v_and_b32_e32 v251, 0xff, v251
	v_and_b32_e32 v252, 0xff, v252
	v_lshl_or_b32 v250, v251, 8, v250
	v_lshl_or_b32 v250, v252, 16, v250
	v_lshl_or_b32 v143, v253, 24, v250
	v_pk_fma_f32 v[164:165], v[86:87], v[86:87], v[164:165]
	v_pk_fma_f32 v[166:167], v[88:89], v[88:89], v[166:167]
	global_store_dwordx4 v136, v[144:147], s[86:87] offset:256
	global_store_dwordx2 v137, v[142:143], s[88:89] offset:128
	s_nop 0
	v_add_f32_e32 v164, v164, v165
	v_add_f32_e32 v166, v166, v167
	v_add_f32_e32 v164, v164, v166
	ds_bpermute_b32 v165, v138, v164
	s_waitcnt lgkmcnt(0)
	v_add_f32_e32 v164, v164, v165
	ds_bpermute_b32 v165, v139, v164
	s_waitcnt lgkmcnt(0)
	v_add_f32_e32 v164, v164, v165
	s_and_saveexec_b64 s[32:33], s[6:7]
	global_atomic_add_f32 v134, v164, s[16:17] offset:128
	s_or_b64 exec, exec, s[32:33]
	s_add_u32 s86, s86, 0x20000
	s_addc_u32 s87, s87, 0
	s_add_u32 s88, s88, 0x10000
	s_addc_u32 s89, s89, 0
	global_load_dword v170, v134, s[14:15] offset:640
	global_load_dwordx4 v[218:221], v135, s[84:85]
	global_load_dwordx4 v[222:225], v135, s[84:85] offset:16
	global_load_dwordx4 v[226:229], v135, s[84:85] offset:512
	global_load_dwordx4 v[230:233], v135, s[84:85] offset:528
	s_add_u32 s84, s84, 0x40000
	s_addc_u32 s85, s85, 0
	s_waitcnt vmcnt(30)
; __device__ __forceinline__ u32x4 pack8(const f32x4 a, const f32x4 b) { u32x4 w; w.x = cvt_pk_bf16(a[0], a[1]); w.y = cvt_pk_bf16(a[2], a[3]); w.z = cvt_pk_bf16(b[0], b[1]); w.w = cvt_pk_bf16(b[2], b[3]); return w; }
;     __device__ __forceinline__ void operator()(const f32x4 (&acc)[2][2][4][2], const pg8::Unit& u, int wr, int wc, int fr, int fq) const {
;         const int row0 = u.pm * 256 + wr * 64 + fr, col0 = u.pn * 256 + wc * 32 + 8 * fq;
; #pragma unroll
;         for (int ai = 0; ai < 2; ++ai)
; #pragma unroll
;             for (int mp = 0; mp < 2; ++mp) {
;                 f32x4 xr[2][2][2]; float iqv[2];
; #pragma unroll
;                 for (int mm = 0; mm < 2; ++mm) { const int row = row0 + ai * 128 + (2 * mp + mm) * 16; iqv[mm] = rs0[row];
; #pragma unroll
;                     for (int bj = 0; bj < 2; ++bj) { const size_t off = (size_t)row * DM + col0 + bj * 128; xr[mm][bj][0] = *(const f32x4*)(x + off); xr[mm][bj][1] = *(const f32x4*)(x + off + 4); } }
; #pragma unroll
;                 for (int mm = 0; mm < 2; ++mm) { const int m = 2 * mp + mm, row = row0 + ai * 128 + m * 16; float ss = 0.f; const float iq = (127.f / QCLIP) * iqv[mm];
; #pragma unroll
;                     for (int bj = 0; bj < 2; ++bj) { const size_t off = (size_t)row * DM + col0 + bj * 128;
;                         const f32x4 h0 = xr[mm][bj][0] + acc[ai][bj][m][0], h1 = xr[mm][bj][1] + acc[ai][bj][m][1];
;                         *(u32x4*)(HB + off) = pack8(h0, h1);
;                         { f32x4 q0, q1;
; #pragma unroll
;                           for (int ee = 0; ee < 4; ++ee) { q0[ee] = fminf(fmaxf(rintf(h0[ee] * iq), -127.f), 127.f); q1[ee] = fminf(fmaxf(rintf(h1[ee] * iq), -127.f), 127.f); }
;                           *(u32x2*)(HQ + off) = pack8_i8(q0, q1); }
;                         ss += (h0[0] * h0[0] + h0[1] * h0[1]) + (h0[2] * h0[2] + h0[3] * h0[3]) + (h1[0] * h1[0] + h1[1] * h1[1]) + (h1[2] * h1[2] + h1[3] * h1[3]); }
;                     ss += __shfl_xor(ss, 16); ss += __shfl_xor(ss, 32);
;                     if (fq == 0) unsafeAtomicAdd(rss1 + row, ss); }
;                 asm volatile("" ::: "memory"); }
	v_mul_f32_e32 v140, 0x41e1c71c, v171
	v_pk_add_f32 v[82:83], v[82:83], v[234:235]
	v_pk_add_f32 v[84:85], v[84:85], v[236:237]
	v_cvt_pk_bf16_f32 v144, v82, v83
	v_cvt_pk_bf16_f32 v145, v84, v85
	v_mul_f32_e32 v250, v140, v82
	v_mul_f32_e32 v251, v140, v83
	v_mul_f32_e32 v252, v140, v84
	v_mul_f32_e32 v253, v140, v85
	v_rndne_f32_e32 v250, v250
	v_rndne_f32_e32 v251, v251
	v_rndne_f32_e32 v252, v252
	v_rndne_f32_e32 v253, v253
	v_med3_f32 v250, v250, s71, v183
	v_med3_f32 v251, v251, s71, v183
	v_med3_f32 v252, v252, s71, v183
	v_med3_f32 v253, v253, s71, v183
	v_cvt_i32_f32_e32 v250, v250
	v_cvt_i32_f32_e32 v251, v251
	v_cvt_i32_f32_e32 v252, v252
	v_cvt_i32_f32_e32 v253, v253
	v_and_b32_e32 v250, 0xff, v250
	v_and_b32_e32 v251, 0xff, v251
	v_and_b32_e32 v252, 0xff, v252
	v_lshl_or_b32 v250, v251, 8, v250
	v_lshl_or_b32 v250, v252, 16, v250
	v_lshl_or_b32 v142, v253, 24, v250
	v_pk_mul_f32 v[164:165], v[82:83], v[82:83]
	v_pk_mul_f32 v[166:167], v[84:85], v[84:85]
	v_pk_add_f32 v[78:79], v[78:79], v[238:239]
	v_pk_add_f32 v[80:81], v[80:81], v[240:241]
	v_cvt_pk_bf16_f32 v146, v78, v79
	v_cvt_pk_bf16_f32 v147, v80, v81
	v_mul_f32_e32 v250, v140, v78
	v_mul_f32_e32 v251, v140, v79
	v_mul_f32_e32 v252, v140, v80
	v_mul_f32_e32 v253, v140, v81
	v_rndne_f32_e32 v250, v250
	v_rndne_f32_e32 v251, v251
	v_rndne_f32_e32 v252, v252
	v_rndne_f32_e32 v253, v253
	v_med3_f32 v250, v250, s71, v183
	v_med3_f32 v251, v251, s71, v183
	v_med3_f32 v252, v252, s71, v183
	v_med3_f32 v253, v253, s71, v183
	v_cvt_i32_f32_e32 v250, v250
	v_cvt_i32_f32_e32 v251, v251
	v_cvt_i32_f32_e32 v252, v252
	v_cvt_i32_f32_e32 v253, v253
	v_and_b32_e32 v250, 0xff, v250
	v_and_b32_e32 v251, 0xff, v251
	v_and_b32_e32 v252, 0xff, v252
	v_lshl_or_b32 v250, v251, 8, v250
	v_lshl_or_b32 v250, v252, 16, v250
	v_lshl_or_b32 v143, v253, 24, v250
	v_pk_fma_f32 v[164:165], v[78:79], v[78:79], v[164:165]
	v_pk_fma_f32 v[166:167], v[80:81], v[80:81], v[166:167]
	global_store_dwordx4 v136, v[144:147], s[86:87]
	global_store_dwordx2 v137, v[142:143], s[88:89]
	s_nop 0
	v_pk_add_f32 v[74:75], v[74:75], v[242:243]
	v_pk_add_f32 v[76:77], v[76:77], v[244:245]
	v_cvt_pk_bf16_f32 v144, v74, v75
	v_cvt_pk_bf16_f32 v145, v76, v77
	v_mul_f32_e32 v250, v140, v74
	v_mul_f32_e32 v251, v140, v75
	v_mul_f32_e32 v252, v140, v76
	v_mul_f32_e32 v253, v140, v77
	v_rndne_f32_e32 v250, v250
	v_rndne_f32_e32 v251, v251
	v_rndne_f32_e32 v252, v252
	v_rndne_f32_e32 v253, v253
	v_med3_f32 v250, v250, s71, v183
	v_med3_f32 v251, v251, s71, v183
	v_med3_f32 v252, v252, s71, v183
	v_med3_f32 v253, v253, s71, v183
	v_cvt_i32_f32_e32 v250, v250
	v_cvt_i32_f32_e32 v251, v251
	v_cvt_i32_f32_e32 v252, v252
	v_cvt_i32_f32_e32 v253, v253
	v_and_b32_e32 v250, 0xff, v250
	v_and_b32_e32 v251, 0xff, v251
	v_and_b32_e32 v252, 0xff, v252
	v_lshl_or_b32 v250, v251, 8, v250
	v_lshl_or_b32 v250, v252, 16, v250
	v_lshl_or_b32 v142, v253, 24, v250
	v_pk_fma_f32 v[164:165], v[74:75], v[74:75], v[164:165]
	v_pk_fma_f32 v[166:167], v[76:77], v[76:77], v[166:167]
	v_pk_add_f32 v[70:71], v[70:71], v[246:247]
	v_pk_add_f32 v[72:73], v[72:73], v[248:249]
	v_cvt_pk_bf16_f32 v146, v70, v71
	v_cvt_pk_bf16_f32 v147, v72, v73
	v_mul_f32_e32 v250, v140, v70
	v_mul_f32_e32 v251, v140, v71
	v_mul_f32_e32 v252, v140, v72
	v_mul_f32_e32 v253, v140, v73
	v_rndne_f32_e32 v250, v250
	v_rndne_f32_e32 v251, v251
	v_rndne_f32_e32 v252, v252
	v_rndne_f32_e32 v253, v253
	v_med3_f32 v250, v250, s71, v183
	v_med3_f32 v251, v251, s71, v183
	v_med3_f32 v252, v252, s71, v183
	v_med3_f32 v253, v253, s71, v183
	v_cvt_i32_f32_e32 v250, v250
	v_cvt_i32_f32_e32 v251, v251
	v_cvt_i32_f32_e32 v252, v252
	v_cvt_i32_f32_e32 v253, v253
	v_and_b32_e32 v250, 0xff, v250
	v_and_b32_e32 v251, 0xff, v251
	v_and_b32_e32 v252, 0xff, v252
	v_lshl_or_b32 v250, v251, 8, v250
	v_lshl_or_b32 v250, v252, 16, v250
	v_lshl_or_b32 v143, v253, 24, v250
	v_pk_fma_f32 v[164:165], v[70:71], v[70:71], v[164:165]
	v_pk_fma_f32 v[166:167], v[72:73], v[72:73], v[166:167]
	global_store_dwordx4 v136, v[144:147], s[86:87] offset:256
	global_store_dwordx2 v137, v[142:143], s[88:89] offset:128
	s_nop 0
	v_add_f32_e32 v164, v164, v165
	v_add_f32_e32 v166, v166, v167
	v_add_f32_e32 v164, v164, v166
	ds_bpermute_b32 v165, v138, v164
	s_waitcnt lgkmcnt(0)
	v_add_f32_e32 v164, v164, v165
	ds_bpermute_b32 v165, v139, v164
	s_waitcnt lgkmcnt(0)
	v_add_f32_e32 v164, v164, v165
	s_and_saveexec_b64 s[32:33], s[6:7]
	global_atomic_add_f32 v134, v164, s[16:17] offset:192
	s_or_b64 exec, exec, s[32:33]
	s_add_u32 s86, s86, 0xa0000
	s_addc_u32 s87, s87, 0
	s_add_u32 s88, s88, 0x50000
	s_addc_u32 s89, s89, 0
	global_load_dword v171, v134, s[14:15] offset:704
	global_load_dwordx4 v[234:237], v135, s[84:85]
	global_load_dwordx4 v[238:241], v135, s[84:85] offset:16
	global_load_dwordx4 v[242:245], v135, s[84:85] offset:512
	global_load_dwordx4 v[246:249], v135, s[84:85] offset:528
	s_waitcnt vmcnt(30)
; __device__ __forceinline__ u32x4 pack8(const f32x4 a, const f32x4 b) { u32x4 w; w.x = cvt_pk_bf16(a[0], a[1]); w.y = cvt_pk_bf16(a[2], a[3]); w.z = cvt_pk_bf16(b[0], b[1]); w.w = cvt_pk_bf16(b[2], b[3]); return w; }
;     __device__ __forceinline__ void operator()(const f32x4 (&acc)[2][2][4][2], const pg8::Unit& u, int wr, int wc, int fr, int fq) const {
;     ...
;                 f32x4 xr[2][2][2]; float iqv[2];
; #pragma unroll
;                 for (int mm = 0; mm < 2; ++mm) { const int row = row0 + ai * 128 + (2 * mp + mm) * 16; iqv[mm] = rs0[row];
; #pragma unroll
;                     for (int bj = 0; bj < 2; ++bj) { const size_t off = (size_t)row * DM + col0 + bj * 128; xr[mm][bj][0] = *(const f32x4*)(x + off); xr[mm][bj][1] = *(const f32x4*)(x + off + 4); } }
; #pragma unroll
;                 for (int mm = 0; mm < 2; ++mm) { const int m = 2 * mp + mm, row = row0 + ai * 128 + m * 16; float ss = 0.f; const float iq = (127.f / QCLIP) * iqv[mm];
; #pragma unroll
;                     for (int bj = 0; bj < 2; ++bj) { const size_t off = (size_t)row * DM + col0 + bj * 128;
;                         const f32x4 h0 = xr[mm][bj][0] + acc[ai][bj][m][0], h1 = xr[mm][bj][1] + acc[ai][bj][m][1];
;                         *(u32x4*)(HB + off) = pack8(h0, h1);
;                         { f32x4 q0, q1;
; #pragma unroll
;                           for (int ee = 0; ee < 4; ++ee) { q0[ee] = fminf(fmaxf(rintf(h0[ee] * iq), -127.f), 127.f); q1[ee] = fminf(fmaxf(rintf(h1[ee] * iq), -127.f), 127.f); }
;                           *(u32x2*)(HQ + off) = pack8_i8(q0, q1); }
;                         ss += (h0[0] * h0[0] + h0[1] * h0[1]) + (h0[2] * h0[2] + h0[3] * h0[3]) + (h1[0] * h1[0] + h1[1] * h1[1]) + (h1[2] * h1[2] + h1[3] * h1[3]); }
;                     ss += __shfl_xor(ss, 16); ss += __shfl_xor(ss, 32);
;                     if (fq == 0) unsafeAtomicAdd(rss1 + row, ss); }
;                 asm volatile("" ::: "memory"); }
	v_mul_f32_e32 v140, 0x41e1c71c, v168
	v_pk_add_f32 v[66:67], v[66:67], v[186:187]
	v_pk_add_f32 v[68:69], v[68:69], v[188:189]
	v_cvt_pk_bf16_f32 v144, v66, v67
	v_cvt_pk_bf16_f32 v145, v68, v69
	v_mul_f32_e32 v250, v140, v66
	v_mul_f32_e32 v251, v140, v67
	v_mul_f32_e32 v252, v140, v68
	v_mul_f32_e32 v253, v140, v69
	v_rndne_f32_e32 v250, v250
	v_rndne_f32_e32 v251, v251
	v_rndne_f32_e32 v252, v252
	v_rndne_f32_e32 v253, v253
	v_med3_f32 v250, v250, s71, v183
	v_med3_f32 v251, v251, s71, v183
	v_med3_f32 v252, v252, s71, v183
	v_med3_f32 v253, v253, s71, v183
	v_cvt_i32_f32_e32 v250, v250
	v_cvt_i32_f32_e32 v251, v251
	v_cvt_i32_f32_e32 v252, v252
	v_cvt_i32_f32_e32 v253, v253
	v_and_b32_e32 v250, 0xff, v250
	v_and_b32_e32 v251, 0xff, v251
	v_and_b32_e32 v252, 0xff, v252
	v_lshl_or_b32 v250, v251, 8, v250
	v_lshl_or_b32 v250, v252, 16, v250
	v_lshl_or_b32 v142, v253, 24, v250
	v_pk_mul_f32 v[164:165], v[66:67], v[66:67]
	v_pk_mul_f32 v[166:167], v[68:69], v[68:69]
	v_pk_add_f32 v[62:63], v[62:63], v[190:191]
	v_pk_add_f32 v[64:65], v[64:65], v[192:193]
	v_cvt_pk_bf16_f32 v146, v62, v63
	v_cvt_pk_bf16_f32 v147, v64, v65
	v_mul_f32_e32 v250, v140, v62
	v_mul_f32_e32 v251, v140, v63
	v_mul_f32_e32 v252, v140, v64
	v_mul_f32_e32 v253, v140, v65
	v_rndne_f32_e32 v250, v250
	v_rndne_f32_e32 v251, v251
	v_rndne_f32_e32 v252, v252
	v_rndne_f32_e32 v253, v253
	v_med3_f32 v250, v250, s71, v183
	v_med3_f32 v251, v251, s71, v183
	v_med3_f32 v252, v252, s71, v183
	v_med3_f32 v253, v253, s71, v183
	v_cvt_i32_f32_e32 v250, v250
	v_cvt_i32_f32_e32 v251, v251
	v_cvt_i32_f32_e32 v252, v252
	v_cvt_i32_f32_e32 v253, v253
	v_and_b32_e32 v250, 0xff, v250
	v_and_b32_e32 v251, 0xff, v251
	v_and_b32_e32 v252, 0xff, v252
	v_lshl_or_b32 v250, v251, 8, v250
	v_lshl_or_b32 v250, v252, 16, v250
	v_lshl_or_b32 v143, v253, 24, v250
	v_pk_fma_f32 v[164:165], v[62:63], v[62:63], v[164:165]
	v_pk_fma_f32 v[166:167], v[64:65], v[64:65], v[166:167]
	global_store_dwordx4 v136, v[144:147], s[86:87]
	global_store_dwordx2 v137, v[142:143], s[88:89]
	s_nop 0
	v_pk_add_f32 v[58:59], v[58:59], v[194:195]
	v_pk_add_f32 v[60:61], v[60:61], v[196:197]
	v_cvt_pk_bf16_f32 v144, v58, v59
	v_cvt_pk_bf16_f32 v145, v60, v61
	v_mul_f32_e32 v250, v140, v58
	v_mul_f32_e32 v251, v140, v59
	v_mul_f32_e32 v252, v140, v60
	v_mul_f32_e32 v253, v140, v61
	v_rndne_f32_e32 v250, v250
	v_rndne_f32_e32 v251, v251
	v_rndne_f32_e32 v252, v252
	v_rndne_f32_e32 v253, v253
	v_med3_f32 v250, v250, s71, v183
	v_med3_f32 v251, v251, s71, v183
	v_med3_f32 v252, v252, s71, v183
	v_med3_f32 v253, v253, s71, v183
	v_cvt_i32_f32_e32 v250, v250
	v_cvt_i32_f32_e32 v251, v251
	v_cvt_i32_f32_e32 v252, v252
	v_cvt_i32_f32_e32 v253, v253
	v_and_b32_e32 v250, 0xff, v250
	v_and_b32_e32 v251, 0xff, v251
	v_and_b32_e32 v252, 0xff, v252
	v_lshl_or_b32 v250, v251, 8, v250
	v_lshl_or_b32 v250, v252, 16, v250
	v_lshl_or_b32 v142, v253, 24, v250
	v_pk_fma_f32 v[164:165], v[58:59], v[58:59], v[164:165]
	v_pk_fma_f32 v[166:167], v[60:61], v[60:61], v[166:167]
	v_pk_add_f32 v[54:55], v[54:55], v[198:199]
	v_pk_add_f32 v[56:57], v[56:57], v[200:201]
	v_cvt_pk_bf16_f32 v146, v54, v55
	v_cvt_pk_bf16_f32 v147, v56, v57
	v_mul_f32_e32 v250, v140, v54
	v_mul_f32_e32 v251, v140, v55
	v_mul_f32_e32 v252, v140, v56
	v_mul_f32_e32 v253, v140, v57
	v_rndne_f32_e32 v250, v250
	v_rndne_f32_e32 v251, v251
	v_rndne_f32_e32 v252, v252
	v_rndne_f32_e32 v253, v253
	v_med3_f32 v250, v250, s71, v183
	v_med3_f32 v251, v251, s71, v183
	v_med3_f32 v252, v252, s71, v183
	v_med3_f32 v253, v253, s71, v183
	v_cvt_i32_f32_e32 v250, v250
	v_cvt_i32_f32_e32 v251, v251
	v_cvt_i32_f32_e32 v252, v252
	v_cvt_i32_f32_e32 v253, v253
	v_and_b32_e32 v250, 0xff, v250
	v_and_b32_e32 v251, 0xff, v251
	v_and_b32_e32 v252, 0xff, v252
	v_lshl_or_b32 v250, v251, 8, v250
	v_lshl_or_b32 v250, v252, 16, v250
	v_lshl_or_b32 v143, v253, 24, v250
	v_pk_fma_f32 v[164:165], v[54:55], v[54:55], v[164:165]
	v_pk_fma_f32 v[166:167], v[56:57], v[56:57], v[166:167]
	global_store_dwordx4 v136, v[144:147], s[86:87] offset:256
	global_store_dwordx2 v137, v[142:143], s[88:89] offset:128
	s_nop 0
	v_add_f32_e32 v164, v164, v165
	v_add_f32_e32 v166, v166, v167
	v_add_f32_e32 v164, v164, v166
	ds_bpermute_b32 v165, v138, v164
	s_waitcnt lgkmcnt(0)
	v_add_f32_e32 v164, v164, v165
	ds_bpermute_b32 v165, v139, v164
	s_waitcnt lgkmcnt(0)
	v_add_f32_e32 v164, v164, v165
	s_and_saveexec_b64 s[32:33], s[6:7]
	global_atomic_add_f32 v134, v164, s[16:17] offset:512
	s_or_b64 exec, exec, s[32:33]
	s_add_u32 s86, s86, 0x20000
	s_addc_u32 s87, s87, 0
	s_add_u32 s88, s88, 0x10000
	s_addc_u32 s89, s89, 0
	s_waitcnt vmcnt(25)
; __device__ __forceinline__ u32x4 pack8(const f32x4 a, const f32x4 b) { u32x4 w; w.x = cvt_pk_bf16(a[0], a[1]); w.y = cvt_pk_bf16(a[2], a[3]); w.z = cvt_pk_bf16(b[0], b[1]); w.w = cvt_pk_bf16(b[2], b[3]); return w; }
;     __device__ __forceinline__ void operator()(const f32x4 (&acc)[2][2][4][2], const pg8::Unit& u, int wr, int wc, int fr, int fq) const {
;     ...
;                 f32x4 xr[2][2][2]; float iqv[2];
; #pragma unroll
;                 for (int mm = 0; mm < 2; ++mm) { const int row = row0 + ai * 128 + (2 * mp + mm) * 16; iqv[mm] = rs0[row];
; #pragma unroll
;                     for (int bj = 0; bj < 2; ++bj) { const size_t off = (size_t)row * DM + col0 + bj * 128; xr[mm][bj][0] = *(const f32x4*)(x + off); xr[mm][bj][1] = *(const f32x4*)(x + off + 4); } }
; #pragma unroll
;                 for (int mm = 0; mm < 2; ++mm) { const int m = 2 * mp + mm, row = row0 + ai * 128 + m * 16; float ss = 0.f; const float iq = (127.f / QCLIP) * iqv[mm];
; #pragma unroll
;                     for (int bj = 0; bj < 2; ++bj) { const size_t off = (size_t)row * DM + col0 + bj * 128;
;                         const f32x4 h0 = xr[mm][bj][0] + acc[ai][bj][m][0], h1 = xr[mm][bj][1] + acc[ai][bj][m][1];
;                         *(u32x4*)(HB + off) = pack8(h0, h1);
;                         { f32x4 q0, q1;
; #pragma unroll
;                           for (int ee = 0; ee < 4; ++ee) { q0[ee] = fminf(fmaxf(rintf(h0[ee] * iq), -127.f), 127.f); q1[ee] = fminf(fmaxf(rintf(h1[ee] * iq), -127.f), 127.f); }
;                           *(u32x2*)(HQ + off) = pack8_i8(q0, q1); }
;                         ss += (h0[0] * h0[0] + h0[1] * h0[1]) + (h0[2] * h0[2] + h0[3] * h0[3]) + (h1[0] * h1[0] + h1[1] * h1[1]) + (h1[2] * h1[2] + h1[3] * h1[3]); }
;                     ss += __shfl_xor(ss, 16); ss += __shfl_xor(ss, 32);
;                     if (fq == 0) unsafeAtomicAdd(rss1 + row, ss); }
;                 asm volatile("" ::: "memory"); }
	v_mul_f32_e32 v140, 0x41e1c71c, v169
	v_pk_add_f32 v[50:51], v[50:51], v[202:203]
	v_pk_add_f32 v[52:53], v[52:53], v[204:205]
	v_cvt_pk_bf16_f32 v144, v50, v51
	v_cvt_pk_bf16_f32 v145, v52, v53
	v_mul_f32_e32 v250, v140, v50
	v_mul_f32_e32 v251, v140, v51
	v_mul_f32_e32 v252, v140, v52
	v_mul_f32_e32 v253, v140, v53
	v_rndne_f32_e32 v250, v250
	v_rndne_f32_e32 v251, v251
	v_rndne_f32_e32 v252, v252
	v_rndne_f32_e32 v253, v253
	v_med3_f32 v250, v250, s71, v183
	v_med3_f32 v251, v251, s71, v183
	v_med3_f32 v252, v252, s71, v183
	v_med3_f32 v253, v253, s71, v183
	v_cvt_i32_f32_e32 v250, v250
	v_cvt_i32_f32_e32 v251, v251
	v_cvt_i32_f32_e32 v252, v252
	v_cvt_i32_f32_e32 v253, v253
	v_and_b32_e32 v250, 0xff, v250
	v_and_b32_e32 v251, 0xff, v251
	v_and_b32_e32 v252, 0xff, v252
	v_lshl_or_b32 v250, v251, 8, v250
	v_lshl_or_b32 v250, v252, 16, v250
	v_lshl_or_b32 v142, v253, 24, v250
	v_pk_mul_f32 v[164:165], v[50:51], v[50:51]
	v_pk_mul_f32 v[166:167], v[52:53], v[52:53]
	v_pk_add_f32 v[46:47], v[46:47], v[206:207]
	v_pk_add_f32 v[48:49], v[48:49], v[208:209]
	v_cvt_pk_bf16_f32 v146, v46, v47
	v_cvt_pk_bf16_f32 v147, v48, v49
	v_mul_f32_e32 v250, v140, v46
	v_mul_f32_e32 v251, v140, v47
	v_mul_f32_e32 v252, v140, v48
	v_mul_f32_e32 v253, v140, v49
	v_rndne_f32_e32 v250, v250
	v_rndne_f32_e32 v251, v251
	v_rndne_f32_e32 v252, v252
	v_rndne_f32_e32 v253, v253
	v_med3_f32 v250, v250, s71, v183
	v_med3_f32 v251, v251, s71, v183
	v_med3_f32 v252, v252, s71, v183
	v_med3_f32 v253, v253, s71, v183
	v_cvt_i32_f32_e32 v250, v250
	v_cvt_i32_f32_e32 v251, v251
	v_cvt_i32_f32_e32 v252, v252
	v_cvt_i32_f32_e32 v253, v253
	v_and_b32_e32 v250, 0xff, v250
	v_and_b32_e32 v251, 0xff, v251
	v_and_b32_e32 v252, 0xff, v252
	v_lshl_or_b32 v250, v251, 8, v250
	v_lshl_or_b32 v250, v252, 16, v250
	v_lshl_or_b32 v143, v253, 24, v250
	v_pk_fma_f32 v[164:165], v[46:47], v[46:47], v[164:165]
	v_pk_fma_f32 v[166:167], v[48:49], v[48:49], v[166:167]
	global_store_dwordx4 v136, v[144:147], s[86:87]
	global_store_dwordx2 v137, v[142:143], s[88:89]
	s_nop 0
	v_pk_add_f32 v[42:43], v[42:43], v[210:211]
	v_pk_add_f32 v[44:45], v[44:45], v[212:213]
	v_cvt_pk_bf16_f32 v144, v42, v43
	v_cvt_pk_bf16_f32 v145, v44, v45
	v_mul_f32_e32 v250, v140, v42
	v_mul_f32_e32 v251, v140, v43
	v_mul_f32_e32 v252, v140, v44
	v_mul_f32_e32 v253, v140, v45
	v_rndne_f32_e32 v250, v250
	v_rndne_f32_e32 v251, v251
	v_rndne_f32_e32 v252, v252
	v_rndne_f32_e32 v253, v253
	v_med3_f32 v250, v250, s71, v183
	v_med3_f32 v251, v251, s71, v183
	v_med3_f32 v252, v252, s71, v183
	v_med3_f32 v253, v253, s71, v183
	v_cvt_i32_f32_e32 v250, v250
	v_cvt_i32_f32_e32 v251, v251
	v_cvt_i32_f32_e32 v252, v252
	v_cvt_i32_f32_e32 v253, v253
	v_and_b32_e32 v250, 0xff, v250
	v_and_b32_e32 v251, 0xff, v251
	v_and_b32_e32 v252, 0xff, v252
	v_lshl_or_b32 v250, v251, 8, v250
	v_lshl_or_b32 v250, v252, 16, v250
	v_lshl_or_b32 v142, v253, 24, v250
	v_pk_fma_f32 v[164:165], v[42:43], v[42:43], v[164:165]
	v_pk_fma_f32 v[166:167], v[44:45], v[44:45], v[166:167]
	v_pk_add_f32 v[38:39], v[38:39], v[214:215]
	v_pk_add_f32 v[40:41], v[40:41], v[216:217]
	v_cvt_pk_bf16_f32 v146, v38, v39
	v_cvt_pk_bf16_f32 v147, v40, v41
	v_mul_f32_e32 v250, v140, v38
	v_mul_f32_e32 v251, v140, v39
	v_mul_f32_e32 v252, v140, v40
	v_mul_f32_e32 v253, v140, v41
	v_rndne_f32_e32 v250, v250
	v_rndne_f32_e32 v251, v251
	v_rndne_f32_e32 v252, v252
	v_rndne_f32_e32 v253, v253
	v_med3_f32 v250, v250, s71, v183
	v_med3_f32 v251, v251, s71, v183
	v_med3_f32 v252, v252, s71, v183
	v_med3_f32 v253, v253, s71, v183
	v_cvt_i32_f32_e32 v250, v250
	v_cvt_i32_f32_e32 v251, v251
	v_cvt_i32_f32_e32 v252, v252
	v_cvt_i32_f32_e32 v253, v253
	v_and_b32_e32 v250, 0xff, v250
	v_and_b32_e32 v251, 0xff, v251
	v_and_b32_e32 v252, 0xff, v252
	v_lshl_or_b32 v250, v251, 8, v250
	v_lshl_or_b32 v250, v252, 16, v250
	v_lshl_or_b32 v143, v253, 24, v250
	v_pk_fma_f32 v[164:165], v[38:39], v[38:39], v[164:165]
	v_pk_fma_f32 v[166:167], v[40:41], v[40:41], v[166:167]
	global_store_dwordx4 v136, v[144:147], s[86:87] offset:256
	global_store_dwordx2 v137, v[142:143], s[88:89] offset:128
	s_nop 0
	v_add_f32_e32 v164, v164, v165
	v_add_f32_e32 v166, v166, v167
	v_add_f32_e32 v164, v164, v166
	ds_bpermute_b32 v165, v138, v164
	s_waitcnt lgkmcnt(0)
	v_add_f32_e32 v164, v164, v165
	ds_bpermute_b32 v165, v139, v164
	s_waitcnt lgkmcnt(0)
	v_add_f32_e32 v164, v164, v165
	s_and_saveexec_b64 s[32:33], s[6:7]
	global_atomic_add_f32 v134, v164, s[16:17] offset:576
	s_or_b64 exec, exec, s[32:33]
	s_add_u32 s86, s86, 0x20000
	s_addc_u32 s87, s87, 0
	s_add_u32 s88, s88, 0x10000
	s_addc_u32 s89, s89, 0
	s_waitcnt vmcnt(20)
; __device__ __forceinline__ u32x4 pack8(const f32x4 a, const f32x4 b) { u32x4 w; w.x = cvt_pk_bf16(a[0], a[1]); w.y = cvt_pk_bf16(a[2], a[3]); w.z = cvt_pk_bf16(b[0], b[1]); w.w = cvt_pk_bf16(b[2], b[3]); return w; }
;     __device__ __forceinline__ void operator()(const f32x4 (&acc)[2][2][4][2], const pg8::Unit& u, int wr, int wc, int fr, int fq) const {
;     ...
;                 f32x4 xr[2][2][2]; float iqv[2];
; #pragma unroll
;                 for (int mm = 0; mm < 2; ++mm) { const int row = row0 + ai * 128 + (2 * mp + mm) * 16; iqv[mm] = rs0[row];
; #pragma unroll
;                     for (int bj = 0; bj < 2; ++bj) { const size_t off = (size_t)row * DM + col0 + bj * 128; xr[mm][bj][0] = *(const f32x4*)(x + off); xr[mm][bj][1] = *(const f32x4*)(x + off + 4); } }
; #pragma unroll
;                 for (int mm = 0; mm < 2; ++mm) { const int m = 2 * mp + mm, row = row0 + ai * 128 + m * 16; float ss = 0.f; const float iq = (127.f / QCLIP) * iqv[mm];
; #pragma unroll
;                     for (int bj = 0; bj < 2; ++bj) { const size_t off = (size_t)row * DM + col0 + bj * 128;
;                         const f32x4 h0 = xr[mm][bj][0] + acc[ai][bj][m][0], h1 = xr[mm][bj][1] + acc[ai][bj][m][1];
;                         *(u32x4*)(HB + off) = pack8(h0, h1);
;                         { f32x4 q0, q1;
; #pragma unroll
;                           for (int ee = 0; ee < 4; ++ee) { q0[ee] = fminf(fmaxf(rintf(h0[ee] * iq), -127.f), 127.f); q1[ee] = fminf(fmaxf(rintf(h1[ee] * iq), -127.f), 127.f); }
;                           *(u32x2*)(HQ + off) = pack8_i8(q0, q1); }
;                         ss += (h0[0] * h0[0] + h0[1] * h0[1]) + (h0[2] * h0[2] + h0[3] * h0[3]) + (h1[0] * h1[0] + h1[1] * h1[1]) + (h1[2] * h1[2] + h1[3] * h1[3]); }
;                     ss += __shfl_xor(ss, 16); ss += __shfl_xor(ss, 32);
;                     if (fq == 0) unsafeAtomicAdd(rss1 + row, ss); }
;                 asm volatile("" ::: "memory"); }
	v_mul_f32_e32 v140, 0x41e1c71c, v170
	v_pk_add_f32 v[34:35], v[34:35], v[218:219]
	v_pk_add_f32 v[36:37], v[36:37], v[220:221]
	v_cvt_pk_bf16_f32 v144, v34, v35
	v_cvt_pk_bf16_f32 v145, v36, v37
	v_mul_f32_e32 v250, v140, v34
	v_mul_f32_e32 v251, v140, v35
	v_mul_f32_e32 v252, v140, v36
	v_mul_f32_e32 v253, v140, v37
	v_rndne_f32_e32 v250, v250
	v_rndne_f32_e32 v251, v251
	v_rndne_f32_e32 v252, v252
	v_rndne_f32_e32 v253, v253
	v_med3_f32 v250, v250, s71, v183
	v_med3_f32 v251, v251, s71, v183
	v_med3_f32 v252, v252, s71, v183
	v_med3_f32 v253, v253, s71, v183
	v_cvt_i32_f32_e32 v250, v250
	v_cvt_i32_f32_e32 v251, v251
	v_cvt_i32_f32_e32 v252, v252
	v_cvt_i32_f32_e32 v253, v253
	v_and_b32_e32 v250, 0xff, v250
	v_and_b32_e32 v251, 0xff, v251
	v_and_b32_e32 v252, 0xff, v252
	v_lshl_or_b32 v250, v251, 8, v250
	v_lshl_or_b32 v250, v252, 16, v250
	v_lshl_or_b32 v142, v253, 24, v250
	v_pk_mul_f32 v[164:165], v[34:35], v[34:35]
	v_pk_mul_f32 v[166:167], v[36:37], v[36:37]
	v_pk_add_f32 v[30:31], v[30:31], v[222:223]
	v_pk_add_f32 v[32:33], v[32:33], v[224:225]
	v_cvt_pk_bf16_f32 v146, v30, v31
	v_cvt_pk_bf16_f32 v147, v32, v33
	v_mul_f32_e32 v250, v140, v30
	v_mul_f32_e32 v251, v140, v31
	v_mul_f32_e32 v252, v140, v32
	v_mul_f32_e32 v253, v140, v33
	v_rndne_f32_e32 v250, v250
	v_rndne_f32_e32 v251, v251
	v_rndne_f32_e32 v252, v252
	v_rndne_f32_e32 v253, v253
	v_med3_f32 v250, v250, s71, v183
	v_med3_f32 v251, v251, s71, v183
	v_med3_f32 v252, v252, s71, v183
	v_med3_f32 v253, v253, s71, v183
	v_cvt_i32_f32_e32 v250, v250
	v_cvt_i32_f32_e32 v251, v251
	v_cvt_i32_f32_e32 v252, v252
	v_cvt_i32_f32_e32 v253, v253
	v_and_b32_e32 v250, 0xff, v250
	v_and_b32_e32 v251, 0xff, v251
	v_and_b32_e32 v252, 0xff, v252
	v_lshl_or_b32 v250, v251, 8, v250
	v_lshl_or_b32 v250, v252, 16, v250
	v_lshl_or_b32 v143, v253, 24, v250
	v_pk_fma_f32 v[164:165], v[30:31], v[30:31], v[164:165]
	v_pk_fma_f32 v[166:167], v[32:33], v[32:33], v[166:167]
	global_store_dwordx4 v136, v[144:147], s[86:87]
	global_store_dwordx2 v137, v[142:143], s[88:89]
	s_nop 0
	v_pk_add_f32 v[26:27], v[26:27], v[226:227]
	v_pk_add_f32 v[28:29], v[28:29], v[228:229]
	v_cvt_pk_bf16_f32 v144, v26, v27
	v_cvt_pk_bf16_f32 v145, v28, v29
	v_mul_f32_e32 v250, v140, v26
	v_mul_f32_e32 v251, v140, v27
	v_mul_f32_e32 v252, v140, v28
	v_mul_f32_e32 v253, v140, v29
	v_rndne_f32_e32 v250, v250
	v_rndne_f32_e32 v251, v251
	v_rndne_f32_e32 v252, v252
	v_rndne_f32_e32 v253, v253
	v_med3_f32 v250, v250, s71, v183
	v_med3_f32 v251, v251, s71, v183
	v_med3_f32 v252, v252, s71, v183
	v_med3_f32 v253, v253, s71, v183
	v_cvt_i32_f32_e32 v250, v250
	v_cvt_i32_f32_e32 v251, v251
	v_cvt_i32_f32_e32 v252, v252
	v_cvt_i32_f32_e32 v253, v253
	v_and_b32_e32 v250, 0xff, v250
	v_and_b32_e32 v251, 0xff, v251
	v_and_b32_e32 v252, 0xff, v252
	v_lshl_or_b32 v250, v251, 8, v250
	v_lshl_or_b32 v250, v252, 16, v250
	v_lshl_or_b32 v142, v253, 24, v250
	v_pk_fma_f32 v[164:165], v[26:27], v[26:27], v[164:165]
	v_pk_fma_f32 v[166:167], v[28:29], v[28:29], v[166:167]
	v_pk_add_f32 v[22:23], v[22:23], v[230:231]
	v_pk_add_f32 v[24:25], v[24:25], v[232:233]
	v_cvt_pk_bf16_f32 v146, v22, v23
	v_cvt_pk_bf16_f32 v147, v24, v25
	v_mul_f32_e32 v250, v140, v22
	v_mul_f32_e32 v251, v140, v23
	v_mul_f32_e32 v252, v140, v24
	v_mul_f32_e32 v253, v140, v25
	v_rndne_f32_e32 v250, v250
	v_rndne_f32_e32 v251, v251
	v_rndne_f32_e32 v252, v252
	v_rndne_f32_e32 v253, v253
	v_med3_f32 v250, v250, s71, v183
	v_med3_f32 v251, v251, s71, v183
	v_med3_f32 v252, v252, s71, v183
	v_med3_f32 v253, v253, s71, v183
	v_cvt_i32_f32_e32 v250, v250
	v_cvt_i32_f32_e32 v251, v251
	v_cvt_i32_f32_e32 v252, v252
	v_cvt_i32_f32_e32 v253, v253
	v_and_b32_e32 v250, 0xff, v250
	v_and_b32_e32 v251, 0xff, v251
	v_and_b32_e32 v252, 0xff, v252
	v_lshl_or_b32 v250, v251, 8, v250
	v_lshl_or_b32 v250, v252, 16, v250
	v_lshl_or_b32 v143, v253, 24, v250
	v_pk_fma_f32 v[164:165], v[22:23], v[22:23], v[164:165]
	v_pk_fma_f32 v[166:167], v[24:25], v[24:25], v[166:167]
	global_store_dwordx4 v136, v[144:147], s[86:87] offset:256
	global_store_dwordx2 v137, v[142:143], s[88:89] offset:128
	s_nop 0
	v_add_f32_e32 v164, v164, v165
	v_add_f32_e32 v166, v166, v167
	v_add_f32_e32 v164, v164, v166
	ds_bpermute_b32 v165, v138, v164
	s_waitcnt lgkmcnt(0)
	v_add_f32_e32 v164, v164, v165
	ds_bpermute_b32 v165, v139, v164
	s_waitcnt lgkmcnt(0)
	v_add_f32_e32 v164, v164, v165
	s_and_saveexec_b64 s[32:33], s[6:7]
	global_atomic_add_f32 v134, v164, s[16:17] offset:640
	s_or_b64 exec, exec, s[32:33]
	s_add_u32 s86, s86, 0x20000
	s_addc_u32 s87, s87, 0
	s_add_u32 s88, s88, 0x10000
	s_addc_u32 s89, s89, 0
	s_waitcnt vmcnt(15)
; __device__ __forceinline__ u32x4 pack8(const f32x4 a, const f32x4 b) { u32x4 w; w.x = cvt_pk_bf16(a[0], a[1]); w.y = cvt_pk_bf16(a[2], a[3]); w.z = cvt_pk_bf16(b[0], b[1]); w.w = cvt_pk_bf16(b[2], b[3]); return w; }
;     __device__ __forceinline__ void operator()(const f32x4 (&acc)[2][2][4][2], const pg8::Unit& u, int wr, int wc, int fr, int fq) const {
;     ...
;                 f32x4 xr[2][2][2]; float iqv[2];
; #pragma unroll
;                 for (int mm = 0; mm < 2; ++mm) { const int row = row0 + ai * 128 + (2 * mp + mm) * 16; iqv[mm] = rs0[row];
; #pragma unroll
;                     for (int bj = 0; bj < 2; ++bj) { const size_t off = (size_t)row * DM + col0 + bj * 128; xr[mm][bj][0] = *(const f32x4*)(x + off); xr[mm][bj][1] = *(const f32x4*)(x + off + 4); } }
; #pragma unroll
;                 for (int mm = 0; mm < 2; ++mm) { const int m = 2 * mp + mm, row = row0 + ai * 128 + m * 16; float ss = 0.f; const float iq = (127.f / QCLIP) * iqv[mm];
; #pragma unroll
;                     for (int bj = 0; bj < 2; ++bj) { const size_t off = (size_t)row * DM + col0 + bj * 128;
;                         const f32x4 h0 = xr[mm][bj][0] + acc[ai][bj][m][0], h1 = xr[mm][bj][1] + acc[ai][bj][m][1];
;                         *(u32x4*)(HB + off) = pack8(h0, h1);
;                         { f32x4 q0, q1;
; #pragma unroll
;                           for (int ee = 0; ee < 4; ++ee) { q0[ee] = fminf(fmaxf(rintf(h0[ee] * iq), -127.f), 127.f); q1[ee] = fminf(fmaxf(rintf(h1[ee] * iq), -127.f), 127.f); }
;                           *(u32x2*)(HQ + off) = pack8_i8(q0, q1); }
;                         ss += (h0[0] * h0[0] + h0[1] * h0[1]) + (h0[2] * h0[2] + h0[3] * h0[3]) + (h1[0] * h1[0] + h1[1] * h1[1]) + (h1[2] * h1[2] + h1[3] * h1[3]); }
;                     ss += __shfl_xor(ss, 16); ss += __shfl_xor(ss, 32);
;                     if (fq == 0) unsafeAtomicAdd(rss1 + row, ss); }
;                 asm volatile("" ::: "memory"); }
	v_mul_f32_e32 v140, 0x41e1c71c, v171
	v_pk_add_f32 v[18:19], v[18:19], v[234:235]
	v_pk_add_f32 v[20:21], v[20:21], v[236:237]
	v_cvt_pk_bf16_f32 v144, v18, v19
	v_cvt_pk_bf16_f32 v145, v20, v21
	v_mul_f32_e32 v250, v140, v18
	v_mul_f32_e32 v251, v140, v19
	v_mul_f32_e32 v252, v140, v20
	v_mul_f32_e32 v253, v140, v21
	v_rndne_f32_e32 v250, v250
	v_rndne_f32_e32 v251, v251
	v_rndne_f32_e32 v252, v252
	v_rndne_f32_e32 v253, v253
	v_med3_f32 v250, v250, s71, v183
	v_med3_f32 v251, v251, s71, v183
	v_med3_f32 v252, v252, s71, v183
	v_med3_f32 v253, v253, s71, v183
	v_cvt_i32_f32_e32 v250, v250
	v_cvt_i32_f32_e32 v251, v251
	v_cvt_i32_f32_e32 v252, v252
	v_cvt_i32_f32_e32 v253, v253
	v_and_b32_e32 v250, 0xff, v250
	v_and_b32_e32 v251, 0xff, v251
	v_and_b32_e32 v252, 0xff, v252
	v_lshl_or_b32 v250, v251, 8, v250
	v_lshl_or_b32 v250, v252, 16, v250
	v_lshl_or_b32 v142, v253, 24, v250
	v_pk_mul_f32 v[164:165], v[18:19], v[18:19]
	v_pk_mul_f32 v[166:167], v[20:21], v[20:21]
	v_pk_add_f32 v[14:15], v[14:15], v[238:239]
	v_pk_add_f32 v[16:17], v[16:17], v[240:241]
	v_cvt_pk_bf16_f32 v146, v14, v15
	v_cvt_pk_bf16_f32 v147, v16, v17
	v_mul_f32_e32 v250, v140, v14
	v_mul_f32_e32 v251, v140, v15
	v_mul_f32_e32 v252, v140, v16
	v_mul_f32_e32 v253, v140, v17
	v_rndne_f32_e32 v250, v250
	v_rndne_f32_e32 v251, v251
	v_rndne_f32_e32 v252, v252
	v_rndne_f32_e32 v253, v253
	v_med3_f32 v250, v250, s71, v183
	v_med3_f32 v251, v251, s71, v183
	v_med3_f32 v252, v252, s71, v183
	v_med3_f32 v253, v253, s71, v183
	v_cvt_i32_f32_e32 v250, v250
	v_cvt_i32_f32_e32 v251, v251
	v_cvt_i32_f32_e32 v252, v252
	v_cvt_i32_f32_e32 v253, v253
	v_and_b32_e32 v250, 0xff, v250
	v_and_b32_e32 v251, 0xff, v251
	v_and_b32_e32 v252, 0xff, v252
	v_lshl_or_b32 v250, v251, 8, v250
	v_lshl_or_b32 v250, v252, 16, v250
	v_lshl_or_b32 v143, v253, 24, v250
	v_pk_fma_f32 v[164:165], v[14:15], v[14:15], v[164:165]
	v_pk_fma_f32 v[166:167], v[16:17], v[16:17], v[166:167]
	global_store_dwordx4 v136, v[144:147], s[86:87]
	global_store_dwordx2 v137, v[142:143], s[88:89]
	s_nop 0
	v_pk_add_f32 v[10:11], v[10:11], v[242:243]
	v_pk_add_f32 v[12:13], v[12:13], v[244:245]
	v_cvt_pk_bf16_f32 v144, v10, v11
	v_cvt_pk_bf16_f32 v145, v12, v13
	v_mul_f32_e32 v250, v140, v10
	v_mul_f32_e32 v251, v140, v11
	v_mul_f32_e32 v252, v140, v12
	v_mul_f32_e32 v253, v140, v13
	v_rndne_f32_e32 v250, v250
	v_rndne_f32_e32 v251, v251
	v_rndne_f32_e32 v252, v252
	v_rndne_f32_e32 v253, v253
	v_med3_f32 v250, v250, s71, v183
	v_med3_f32 v251, v251, s71, v183
	v_med3_f32 v252, v252, s71, v183
	v_med3_f32 v253, v253, s71, v183
	v_cvt_i32_f32_e32 v250, v250
	v_cvt_i32_f32_e32 v251, v251
	v_cvt_i32_f32_e32 v252, v252
	v_cvt_i32_f32_e32 v253, v253
	v_and_b32_e32 v250, 0xff, v250
	v_and_b32_e32 v251, 0xff, v251
	v_and_b32_e32 v252, 0xff, v252
	v_lshl_or_b32 v250, v251, 8, v250
	v_lshl_or_b32 v250, v252, 16, v250
	v_lshl_or_b32 v142, v253, 24, v250
	v_pk_fma_f32 v[164:165], v[10:11], v[10:11], v[164:165]
	v_pk_fma_f32 v[166:167], v[12:13], v[12:13], v[166:167]
	v_pk_add_f32 v[6:7], v[6:7], v[246:247]
	v_pk_add_f32 v[8:9], v[8:9], v[248:249]
	v_cvt_pk_bf16_f32 v146, v6, v7
	v_cvt_pk_bf16_f32 v147, v8, v9
	v_mul_f32_e32 v250, v140, v6
	v_mul_f32_e32 v251, v140, v7
	v_mul_f32_e32 v252, v140, v8
	v_mul_f32_e32 v253, v140, v9
	v_rndne_f32_e32 v250, v250
	v_rndne_f32_e32 v251, v251
	v_rndne_f32_e32 v252, v252
	v_rndne_f32_e32 v253, v253
	v_med3_f32 v250, v250, s71, v183
	v_med3_f32 v251, v251, s71, v183
	v_med3_f32 v252, v252, s71, v183
	v_med3_f32 v253, v253, s71, v183
	v_cvt_i32_f32_e32 v250, v250
	v_cvt_i32_f32_e32 v251, v251
	v_cvt_i32_f32_e32 v252, v252
	v_cvt_i32_f32_e32 v253, v253
	v_and_b32_e32 v250, 0xff, v250
	v_and_b32_e32 v251, 0xff, v251
	v_and_b32_e32 v252, 0xff, v252
	v_lshl_or_b32 v250, v251, 8, v250
	v_lshl_or_b32 v250, v252, 16, v250
	v_lshl_or_b32 v143, v253, 24, v250
	v_pk_fma_f32 v[164:165], v[6:7], v[6:7], v[164:165]
	v_pk_fma_f32 v[166:167], v[8:9], v[8:9], v[166:167]
	global_store_dwordx4 v136, v[144:147], s[86:87] offset:256
	global_store_dwordx2 v137, v[142:143], s[88:89] offset:128
	s_nop 0
	v_add_f32_e32 v164, v164, v165
	v_add_f32_e32 v166, v166, v167
	v_add_f32_e32 v164, v164, v166
	ds_bpermute_b32 v165, v138, v164
	s_waitcnt lgkmcnt(0)
	v_add_f32_e32 v164, v164, v165
	ds_bpermute_b32 v165, v139, v164
	s_waitcnt lgkmcnt(0)
	v_add_f32_e32 v164, v164, v165
	s_and_saveexec_b64 s[32:33], s[6:7]
	global_atomic_add_f32 v134, v164, s[16:17] offset:704
	s_or_b64 exec, exec, s[32:33]
	s_nop 1
	s_andn2_b64 vcc, exec, s[8:9]
	s_mov_b64 s[8:9], -1
	s_cbranch_vccnz .LBB0_1124
	s_andn2_b64 vcc, exec, s[24:25]
	s_cbranch_vccnz .LBB0_1123
	s_barrier
	s_branch .LBB0_1123
